# attention loops: LDS-DMA addresses formed as scalar base + 32-bit lane offset (2 SALU) instead of two 64-bit VALU adds per piece
# baseline (speedup 1.0000x reference)
.LBB0_168:
	s_barrier
	s_cmp_lt_u32 s22, s19
	s_mov_b64 s[26:27], -1
	s_cbranch_scc1 .LBB0_174
	s_add_i32 s22, s23, 2
	s_cmp_ge_u32 s22, s17
	s_cbranch_scc1 .LBB0_171
	s_lshl_b32 s26, s48, 14
	s_add_i32 s26, s11, s26
	s_add_i32 s27, s26, 0x2000
	s_add_u32 s100, s8, s80
	s_addc_u32 s101, s9, s81
	s_mov_b32 m0, s26
	s_nop 0
	global_load_lds_dwordx4 v214, s[100:101]
	s_add_u32 s100, s8, s62
	s_addc_u32 s101, s9, s63
	s_mov_b32 m0, s27
	s_nop 0
	global_load_lds_dwordx4 v214, s[100:101]
.LBB0_171:
	s_andn2_b64 vcc, exec, s[88:89]
	s_cbranch_vccnz .LBB0_173
	s_lshl_b32 s26, s31, 14
	s_add_i32 s26, s11, s26
	s_add_u32 s100, s8, s96
	s_addc_u32 s101, s9, s97
	s_add_i32 m0, s26, 0xc000
	s_add_i32 s26, s26, 0xe000
	global_load_lds_dwordx4 v216, s[100:101]
	s_add_u32 s100, s8, s58
	s_addc_u32 s101, s9, s59
	s_mov_b32 m0, s26
	s_nop 0
	global_load_lds_dwordx4 v216, s[100:101]

.LBB0_174:
	s_and_b64 vcc, exec, s[26:27]
	s_cbranch_vccz .LBB0_200
	s_lshl_b32 s22, s49, 14
	s_add_i32 s54, s22, 0
	s_mov_b64 s[26:27], -1
	s_cmp_ge_u32 s23, s19
	v_add_u32_e32 v249, s54, v244
	v_add_u32_e32 v212, s54, v245
	s_cbranch_scc0 .LBB0_185
	ds_read_b128 v[98:101], v249 offset:49152
	ds_read_b128 v[114:117], v249 offset:53248
	ds_read_b128 v[130:133], v249 offset:57344
	ds_read_b128 v[194:197], v249 offset:61440
	s_waitcnt lgkmcnt(0)
	v_mfma_f32_32x32x16_bf16 v[82:97], v[98:101], v[162:165], v[34:49]
	ds_read_b128 v[206:209], v212 offset:49152
	v_mfma_f32_32x32x16_bf16 v[98:113], v[114:117], v[162:165], v[50:65]
	ds_read_b128 v[198:201], v212 offset:53248
	s_add_i32 s22, s23, 2
	s_cmp_lt_u32 s22, s17
	s_cselect_b64 s[26:27], -1, 0
	s_cmp_ge_u32 s22, s17
	s_cbranch_scc1 .LBB0_178
	s_lshl_b32 s40, s48, 14
	s_add_u32 s100, s8, s80
	s_addc_u32 s101, s9, s81
	s_add_i32 m0, s11, s40
	s_nop 0
	global_load_lds_dwordx4 v214, s[100:101]
.LBB0_178:
	v_mfma_f32_32x32x16_bf16 v[114:129], v[130:133], v[162:165], v[18:33]
	ds_read_b128 v[202:205], v212 offset:57344
	v_mfma_f32_32x32x16_bf16 v[130:145], v[194:197], v[162:165], v[2:17]
	ds_read_b128 v[194:197], v212 offset:61440
	s_waitcnt lgkmcnt(0)
	v_mfma_f32_32x32x16_bf16 v[82:97], v[206:209], v[170:173], v[82:97]
	v_add_u32_e32 v250, s54, v246
	ds_read_b128 v[206:209], v250 offset:49152
	v_mfma_f32_32x32x16_bf16 v[98:113], v[198:201], v[170:173], v[98:113]
	ds_read_b128 v[198:201], v250 offset:53248
	s_andn2_b64 vcc, exec, s[26:27]
	s_cbranch_vccnz .LBB0_180
	s_lshl_b32 s26, s48, 14
	s_add_i32 s26, s11, s26
	s_add_u32 s100, s8, s62
	s_addc_u32 s101, s9, s63
	s_add_i32 m0, s26, 0x2000
	s_nop 0
	global_load_lds_dwordx4 v214, s[100:101]
.LBB0_180:
	v_mfma_f32_32x32x16_bf16 v[114:129], v[202:205], v[170:173], v[114:129]
	ds_read_b128 v[202:205], v250 offset:57344
	v_mfma_f32_32x32x16_bf16 v[130:145], v[194:197], v[170:173], v[130:145]
	ds_read_b128 v[194:197], v250 offset:61440
	s_waitcnt lgkmcnt(0)
	v_mfma_f32_32x32x16_bf16 v[82:97], v[206:209], v[178:181], v[82:97]
	v_add_u32_e32 v250, s54, v247
	ds_read_b128 v[206:209], v250 offset:49152
	v_mfma_f32_32x32x16_bf16 v[98:113], v[198:201], v[178:181], v[98:113]
	ds_read_b128 v[198:201], v250 offset:53248
	v_cndmask_b32_e64 v224, 0, 1, s[88:89]
	v_cmp_ne_u32_e64 s[40:41], 1, v224
	s_andn2_b64 vcc, exec, s[88:89]
	s_cbranch_vccnz .LBB0_182
	s_lshl_b32 s26, s31, 14
	s_add_i32 s26, s11, s26
	s_add_u32 s100, s8, s96
	s_addc_u32 s101, s9, s97
	s_add_i32 m0, s26, 0xc000
	s_nop 0
	global_load_lds_dwordx4 v216, s[100:101]
.LBB0_182:
	v_mfma_f32_32x32x16_bf16 v[114:129], v[202:205], v[178:181], v[114:129]
	ds_read_b128 v[202:205], v250 offset:57344
	v_mfma_f32_32x32x16_bf16 v[130:145], v[194:197], v[178:181], v[130:145]
	ds_read_b128 v[194:197], v250 offset:61440
	s_waitcnt lgkmcnt(0)
	v_mfma_f32_32x32x16_bf16 v[82:97], v[206:209], v[186:189], v[82:97]
	v_mfma_f32_32x32x16_bf16 v[98:113], v[198:201], v[186:189], v[98:113]
	s_and_b64 vcc, exec, s[40:41]
	s_cbranch_vccnz .LBB0_184
	s_lshl_b32 s26, s31, 14
	s_add_i32 s26, s11, s26
	s_add_u32 s100, s8, s58
	s_addc_u32 s101, s9, s59
	s_add_i32 m0, s26, 0xe000
	s_nop 0
	global_load_lds_dwordx4 v216, s[100:101]

.LBB0_188:
	s_waitcnt lgkmcnt(0)
	v_mfma_f32_32x32x16_bf16 v[34:49], v[126:129], v[162:165], v[34:49]
	ds_read_b128 v[126:129], v212 offset:49152
	s_nop 0
	v_exp_f32_e32 v130, v82
	v_exp_f32_e32 v131, v83
	v_add_f32_e32 v132, v1, v130
	v_add_f32_e32 v133, v1, v131
	v_cvt_pk_bf16_f32 v166, v130, v131
	v_mfma_f32_32x32x16_bf16 v[50:65], v[122:125], v[162:165], v[50:65]
	ds_read_b128 v[122:125], v212 offset:53248
	v_exp_f32_e32 v134, v84
	v_exp_f32_e32 v135, v85
	s_add_i32 s22, s23, 2
	s_cmp_lt_u32 s22, s17
	v_add_f32_e32 v130, v132, v134
	v_add_f32_e32 v131, v133, v135
	v_cvt_pk_bf16_f32 v167, v134, v135
	s_cselect_b64 s[26:27], -1, 0
	s_cmp_ge_u32 s22, s17
	s_cbranch_scc1 .LBB0_190
	s_lshl_b32 s40, s48, 14
	s_add_u32 s100, s8, s80
	s_addc_u32 s101, s9, s81
	s_add_i32 m0, s11, s40
	s_nop 0
	global_load_lds_dwordx4 v214, s[100:101]
.LBB0_190:
	v_mfma_f32_32x32x16_bf16 v[18:33], v[118:121], v[162:165], v[18:33]
	ds_read_b128 v[118:121], v212 offset:57344
	v_exp_f32_e32 v132, v86
	v_exp_f32_e32 v133, v87
	v_add_f32_e32 v130, v130, v132
	v_add_f32_e32 v131, v131, v133
	v_cvt_pk_bf16_f32 v168, v132, v133
	v_mfma_f32_32x32x16_bf16 v[2:17], v[114:117], v[162:165], v[2:17]
	ds_read_b128 v[114:117], v212 offset:61440
	v_exp_f32_e32 v132, v88
	v_exp_f32_e32 v133, v89
	v_add_f32_e32 v134, v130, v132
	v_add_f32_e32 v131, v131, v133
	v_cvt_pk_bf16_f32 v169, v132, v133
	s_waitcnt lgkmcnt(0)
	v_mfma_f32_32x32x16_bf16 v[34:49], v[126:129], v[170:173], v[34:49]
	v_add_u32_e32 v130, s54, v246
	ds_read_b128 v[126:129], v130 offset:49152
	v_exp_f32_e32 v132, v90
	v_exp_f32_e32 v133, v91
	v_add_f32_e32 v134, v134, v132
	v_add_f32_e32 v135, v131, v133
	v_cvt_pk_bf16_f32 v174, v132, v133
	v_mfma_f32_32x32x16_bf16 v[50:65], v[122:125], v[170:173], v[50:65]
	ds_read_b128 v[122:125], v130 offset:53248
	v_exp_f32_e32 v133, v92
	v_exp_f32_e32 v136, v93
	v_add_f32_e32 v131, v134, v133
	v_add_f32_e32 v132, v135, v136
	s_andn2_b64 vcc, exec, s[26:27]
	v_cvt_pk_bf16_f32 v175, v133, v136
	s_cbranch_vccnz .LBB0_192
	s_lshl_b32 s26, s48, 14
	s_add_i32 s26, s11, s26
	s_add_u32 s100, s8, s62
	s_addc_u32 s101, s9, s63
	s_add_i32 m0, s26, 0x2000
	s_nop 0
	global_load_lds_dwordx4 v214, s[100:101]
.LBB0_192:
	v_mfma_f32_32x32x16_bf16 v[18:33], v[118:121], v[170:173], v[18:33]
	ds_read_b128 v[118:121], v130 offset:57344
	v_exp_f32_e32 v133, v94
	v_exp_f32_e32 v134, v95
	v_add_f32_e32 v131, v131, v133
	v_add_f32_e32 v132, v132, v134
	v_cvt_pk_bf16_f32 v176, v133, v134
	v_mfma_f32_32x32x16_bf16 v[2:17], v[114:117], v[170:173], v[2:17]
	ds_read_b128 v[114:117], v130 offset:61440
	v_exp_f32_e32 v130, v96
	v_exp_f32_e32 v133, v97
	v_add_f32_e32 v131, v131, v130
	v_add_f32_e32 v132, v132, v133
	v_cvt_pk_bf16_f32 v177, v130, v133
	s_waitcnt lgkmcnt(0)
	v_mfma_f32_32x32x16_bf16 v[34:49], v[126:129], v[178:181], v[34:49]
	v_add_u32_e32 v130, s54, v247
	ds_read_b128 v[126:129], v130 offset:49152
	v_exp_f32_e32 v133, v98
	v_exp_f32_e32 v134, v99
	v_add_f32_e32 v131, v131, v133
	v_add_f32_e32 v132, v132, v134
	v_cvt_pk_bf16_f32 v182, v133, v134
	v_mfma_f32_32x32x16_bf16 v[50:65], v[122:125], v[178:181], v[50:65]
	v_exp_f32_e32 v133, v100
	v_exp_f32_e32 v134, v101
	ds_read_b128 v[122:125], v130 offset:53248
	v_add_f32_e32 v131, v131, v133
	v_add_f32_e32 v132, v132, v134
	v_cvt_pk_bf16_f32 v183, v133, v134
	v_cndmask_b32_e64 v133, 0, 1, s[88:89]
	v_cmp_ne_u32_e64 s[40:41], 1, v133
	s_andn2_b64 vcc, exec, s[88:89]
	s_cbranch_vccnz .LBB0_194
	s_lshl_b32 s26, s31, 14
	s_add_i32 s26, s11, s26
	s_add_u32 s100, s8, s96
	s_addc_u32 s101, s9, s97
	s_add_i32 m0, s26, 0xc000
	s_nop 0
	global_load_lds_dwordx4 v216, s[100:101]
.LBB0_194:
	v_mfma_f32_32x32x16_bf16 v[18:33], v[118:121], v[178:181], v[18:33]
	ds_read_b128 v[118:121], v130 offset:57344
	v_exp_f32_e32 v133, v102
	v_exp_f32_e32 v134, v103
	v_add_f32_e32 v131, v131, v133
	v_add_f32_e32 v132, v132, v134
	v_cvt_pk_bf16_f32 v184, v133, v134
	v_mfma_f32_32x32x16_bf16 v[2:17], v[114:117], v[178:181], v[2:17]
	ds_read_b128 v[114:117], v130 offset:61440
	v_exp_f32_e32 v130, v104
	v_exp_f32_e32 v133, v105
	v_add_f32_e32 v131, v131, v130
	v_add_f32_e32 v132, v132, v133
	v_cvt_pk_bf16_f32 v185, v130, v133
	s_waitcnt lgkmcnt(0)
	v_mfma_f32_32x32x16_bf16 v[34:49], v[126:129], v[186:189], v[34:49]
	v_exp_f32_e32 v126, v106
	v_exp_f32_e32 v127, v107
	v_add_f32_e32 v128, v131, v126
	v_add_f32_e32 v129, v132, v127
	v_cvt_pk_bf16_f32 v190, v126, v127
	v_mfma_f32_32x32x16_bf16 v[50:65], v[122:125], v[186:189], v[50:65]
	v_exp_f32_e32 v124, v108
	v_exp_f32_e32 v125, v109
	v_add_f32_e32 v122, v128, v124
	v_add_f32_e32 v123, v129, v125
	s_and_b64 vcc, exec, s[40:41]
	v_cvt_pk_bf16_f32 v191, v124, v125
	s_cbranch_vccnz .LBB0_196
	s_lshl_b32 s26, s31, 14
	s_add_i32 s26, s11, s26
	s_add_u32 s100, s8, s58
	s_addc_u32 s101, s9, s59
	s_add_i32 m0, s26, 0xe000
	s_nop 0
	global_load_lds_dwordx4 v216, s[100:101]

.LBB0_208:
	s_add_i32 s26, s33, 1
	s_cmp_lg_u32 s33, 2
	s_cselect_b32 s33, s26, 0
	s_add_i32 s26, s48, 1
	s_cmp_lg_u32 s48, 2
	s_cselect_b32 s48, s26, 0
	s_add_i32 s26, s49, 1
	s_cmp_lg_u32 s49, 2
	s_cselect_b32 s49, s26, 0
	s_add_i32 s26, s31, 1
	s_barrier
	s_cmp_lg_u32 s31, 2
	s_cselect_b32 s31, s26, 0
	s_cmp_lt_u32 s23, s19
	s_mov_b64 s[26:27], -1
	s_cbranch_scc1 .LBB0_214
	s_add_i32 s26, s23, 3
	s_cmp_gt_u32 s26, s16
	s_cbranch_scc1 .LBB0_211
	s_lshl_b32 s26, s48, 14
	s_add_i32 s26, s11, s26
	s_add_i32 s27, s26, 0x2000
	s_add_u32 s100, s8, s50
	s_addc_u32 s101, s9, s51
	s_mov_b32 m0, s26
	s_nop 0
	global_load_lds_dwordx4 v214, s[100:101]
	s_add_u32 s100, s8, s4
	s_addc_u32 s101, s9, s5
	s_mov_b32 m0, s27
	s_nop 0
	global_load_lds_dwordx4 v214, s[100:101]
.LBB0_211:
	s_andn2_b64 vcc, exec, s[88:89]
	s_cbranch_vccnz .LBB0_213
	s_lshl_b32 s26, s31, 14
	s_add_i32 s26, s11, s26
	s_add_u32 s100, s8, s0
	s_addc_u32 s101, s9, s1
	s_add_i32 m0, s26, 0xc000
	s_add_i32 s26, s26, 0xe000
	global_load_lds_dwordx4 v216, s[100:101]
	s_add_u32 s100, s8, s52
	s_addc_u32 s101, s9, s53
	s_mov_b32 m0, s26
	s_nop 0
	global_load_lds_dwordx4 v216, s[100:101]

.LBB0_214:
	s_and_b64 vcc, exec, s[26:27]
	s_cbranch_vccz .LBB0_240
	s_lshl_b32 s26, s49, 14
	s_add_i32 s40, s23, 1
	s_add_i32 s54, s26, 0
	s_mov_b64 s[26:27], -1
	s_cmp_ge_u32 s40, s19
	v_add_u32_e32 v249, s54, v244
	v_add_u32_e32 v212, s54, v245
	s_cbranch_scc0 .LBB0_225
	ds_read_b128 v[98:101], v249 offset:49152
	ds_read_b128 v[114:117], v249 offset:53248
	ds_read_b128 v[130:133], v249 offset:57344
	ds_read_b128 v[194:197], v249 offset:61440
	s_waitcnt lgkmcnt(0)
	v_mfma_f32_32x32x16_bf16 v[82:97], v[98:101], v[166:169], v[34:49]
	ds_read_b128 v[206:209], v212 offset:49152
	v_mfma_f32_32x32x16_bf16 v[98:113], v[114:117], v[166:169], v[50:65]
	ds_read_b128 v[198:201], v212 offset:53248
	s_add_i32 s40, s23, 3
	s_cmp_le_u32 s40, s16
	s_cselect_b64 s[26:27], -1, 0
	s_cmp_gt_u32 s40, s16
	s_cbranch_scc1 .LBB0_218
	s_lshl_b32 s40, s48, 14
	s_add_u32 s100, s8, s50
	s_addc_u32 s101, s9, s51
	s_add_i32 m0, s11, s40
	s_nop 0
	global_load_lds_dwordx4 v214, s[100:101]
.LBB0_218:
	v_mfma_f32_32x32x16_bf16 v[114:129], v[130:133], v[166:169], v[18:33]
	ds_read_b128 v[202:205], v212 offset:57344
	v_mfma_f32_32x32x16_bf16 v[130:145], v[194:197], v[166:169], v[2:17]
	ds_read_b128 v[194:197], v212 offset:61440
	s_waitcnt lgkmcnt(0)
	v_mfma_f32_32x32x16_bf16 v[82:97], v[206:209], v[174:177], v[82:97]
	v_add_u32_e32 v250, s54, v246
	ds_read_b128 v[206:209], v250 offset:49152
	v_mfma_f32_32x32x16_bf16 v[98:113], v[198:201], v[174:177], v[98:113]
	ds_read_b128 v[198:201], v250 offset:53248
	s_andn2_b64 vcc, exec, s[26:27]
	s_cbranch_vccnz .LBB0_220
	s_lshl_b32 s26, s48, 14
	s_add_i32 s26, s11, s26
	s_add_u32 s100, s8, s4
	s_addc_u32 s101, s9, s5
	s_add_i32 m0, s26, 0x2000
	s_nop 0
	global_load_lds_dwordx4 v214, s[100:101]
.LBB0_220:
	v_mfma_f32_32x32x16_bf16 v[114:129], v[202:205], v[174:177], v[114:129]
	ds_read_b128 v[202:205], v250 offset:57344
	v_mfma_f32_32x32x16_bf16 v[130:145], v[194:197], v[174:177], v[130:145]
	ds_read_b128 v[194:197], v250 offset:61440
	s_waitcnt lgkmcnt(0)
	v_mfma_f32_32x32x16_bf16 v[82:97], v[206:209], v[182:185], v[82:97]
	v_add_u32_e32 v250, s54, v247
	ds_read_b128 v[206:209], v250 offset:49152
	v_mfma_f32_32x32x16_bf16 v[98:113], v[198:201], v[182:185], v[98:113]
	ds_read_b128 v[198:201], v250 offset:53248
	v_cndmask_b32_e64 v224, 0, 1, s[88:89]
	v_cmp_ne_u32_e64 s[40:41], 1, v224
	s_andn2_b64 vcc, exec, s[88:89]
	s_cbranch_vccnz .LBB0_222
	s_lshl_b32 s26, s31, 14
	s_add_i32 s26, s11, s26
	s_add_u32 s100, s8, s0
	s_addc_u32 s101, s9, s1
	s_add_i32 m0, s26, 0xc000
	s_nop 0
	global_load_lds_dwordx4 v216, s[100:101]
.LBB0_222:
	v_mfma_f32_32x32x16_bf16 v[114:129], v[202:205], v[182:185], v[114:129]
	ds_read_b128 v[202:205], v250 offset:57344
	v_mfma_f32_32x32x16_bf16 v[130:145], v[194:197], v[182:185], v[130:145]
	ds_read_b128 v[194:197], v250 offset:61440
	s_waitcnt lgkmcnt(0)
	v_mfma_f32_32x32x16_bf16 v[82:97], v[206:209], v[190:193], v[82:97]
	v_mfma_f32_32x32x16_bf16 v[98:113], v[198:201], v[190:193], v[98:113]
	s_and_b64 vcc, exec, s[40:41]
	s_cbranch_vccnz .LBB0_224
	s_lshl_b32 s26, s31, 14
	s_add_i32 s26, s11, s26
	s_add_u32 s100, s8, s52
	s_addc_u32 s101, s9, s53
	s_add_i32 m0, s26, 0xe000
	s_nop 0
	global_load_lds_dwordx4 v216, s[100:101]

.LBB0_232:
	v_mfma_f32_32x32x16_bf16 v[18:33], v[118:121], v[174:177], v[18:33]
	ds_read_b128 v[118:121], v132 offset:57344
	v_exp_f32_e32 v130, v94
	v_exp_f32_e32 v131, v95
	v_add_f32_e32 v133, v133, v130
	v_add_f32_e32 v134, v134, v131
	v_cvt_pk_bf16_f32 v172, v130, v131
	v_mfma_f32_32x32x16_bf16 v[2:17], v[114:117], v[174:177], v[2:17]
	ds_read_b128 v[114:117], v132 offset:61440
	v_exp_f32_e32 v130, v96
	v_exp_f32_e32 v131, v97
	v_add_f32_e32 v133, v133, v130
	v_add_f32_e32 v134, v134, v131
	v_cvt_pk_bf16_f32 v173, v130, v131
	s_waitcnt lgkmcnt(0)
	v_mfma_f32_32x32x16_bf16 v[34:49], v[126:129], v[182:185], v[34:49]
	v_add_u32_e32 v132, s54, v247
	ds_read_b128 v[126:129], v132 offset:49152
	v_exp_f32_e32 v130, v98
	v_exp_f32_e32 v131, v99
	v_add_f32_e32 v133, v133, v130
	v_add_f32_e32 v134, v134, v131
	v_cvt_pk_bf16_f32 v178, v130, v131
	v_mfma_f32_32x32x16_bf16 v[50:65], v[122:125], v[182:185], v[50:65]
	v_exp_f32_e32 v130, v100
	v_exp_f32_e32 v131, v101
	ds_read_b128 v[122:125], v132 offset:53248
	v_add_f32_e32 v133, v133, v130
	v_add_f32_e32 v134, v134, v131
	v_cvt_pk_bf16_f32 v179, v130, v131
	v_cndmask_b32_e64 v130, 0, 1, s[88:89]
	v_cmp_ne_u32_e64 s[40:41], 1, v130
	s_andn2_b64 vcc, exec, s[88:89]
	v_lshl_add_u64 v[130:131], s[8:9], 0, v[216:217]
	s_cbranch_vccnz .LBB0_234
	s_lshl_b32 s23, s31, 14
	s_add_i32 s23, s11, s23
	s_add_u32 s100, s8, s0
	s_addc_u32 s101, s9, s1
	s_add_i32 m0, s23, 0xc000
	s_nop 0
	global_load_lds_dwordx4 v216, s[100:101]

.LBB0_271:
	s_barrier
	s_cmp_lt_u32 s21, s19
	s_mov_b64 s[26:27], -1
	s_cbranch_scc1 .LBB0_277
	s_add_i32 s21, s22, 2
	s_cmp_ge_u32 s21, s18
	s_cbranch_scc1 .LBB0_274
	s_lshl_b32 s26, s28, 14
	s_add_i32 s26, s10, s26
	s_add_i32 s27, s26, 0x2000
	s_add_u32 s100, s8, s80
	s_addc_u32 s101, s9, s81
	s_mov_b32 m0, s26
	s_nop 0
	global_load_lds_dwordx4 v214, s[100:101]
	s_add_u32 s100, s8, s62
	s_addc_u32 s101, s9, s63
	s_mov_b32 m0, s27
	s_nop 0
	global_load_lds_dwordx4 v214, s[100:101]
.LBB0_274:
	s_andn2_b64 vcc, exec, s[44:45]
	s_cbranch_vccnz .LBB0_276
	s_lshl_b32 s26, s23, 14
	s_add_i32 s26, s10, s26
	s_add_u32 s100, s8, s96
	s_addc_u32 s101, s9, s97
	s_add_i32 m0, s26, 0xc000
	s_add_i32 s26, s26, 0xe000
	global_load_lds_dwordx4 v216, s[100:101]
	s_add_u32 s100, s8, s58
	s_addc_u32 s101, s9, s59
	s_mov_b32 m0, s26
	s_nop 0
	global_load_lds_dwordx4 v216, s[100:101]

.LBB0_277:
	s_and_b64 vcc, exec, s[26:27]
	s_cbranch_vccz .LBB0_303
	s_lshl_b32 s21, s33, 14
	s_add_i32 s36, s21, 0
	s_mov_b64 s[26:27], -1
	s_cmp_ge_u32 s22, s19
	v_add_u32_e32 v212, s36, v245
	v_add_u32_e32 v0, s36, v246
	s_cbranch_scc0 .LBB0_288
	ds_read_b128 v[98:101], v212 offset:49152
	ds_read_b128 v[114:117], v212 offset:53248
	ds_read_b128 v[130:133], v212 offset:57344
	ds_read_b128 v[194:197], v212 offset:61440
	s_waitcnt lgkmcnt(0)
	v_mfma_f32_32x32x16_bf16 v[82:97], v[98:101], v[162:165], v[50:65]
	ds_read_b128 v[206:209], v0 offset:49152
	v_mfma_f32_32x32x16_bf16 v[98:113], v[114:117], v[162:165], v[34:49]
	ds_read_b128 v[198:201], v0 offset:53248
	s_add_i32 s21, s22, 2
	s_cmp_lt_u32 s21, s18
	s_cselect_b64 s[26:27], -1, 0
	s_cmp_ge_u32 s21, s18
	s_cbranch_scc1 .LBB0_281
	s_lshl_b32 s37, s28, 14
	s_add_u32 s100, s8, s80
	s_addc_u32 s101, s9, s81
	s_add_i32 m0, s10, s37
	s_nop 0
	global_load_lds_dwordx4 v214, s[100:101]
.LBB0_281:
	v_mfma_f32_32x32x16_bf16 v[114:129], v[130:133], v[162:165], v[18:33]
	ds_read_b128 v[202:205], v0 offset:57344
	v_mfma_f32_32x32x16_bf16 v[130:145], v[194:197], v[162:165], v[2:17]
	ds_read_b128 v[194:197], v0 offset:61440
	s_waitcnt lgkmcnt(0)
	v_mfma_f32_32x32x16_bf16 v[82:97], v[206:209], v[170:173], v[82:97]
	v_add_u32_e32 v250, s36, v247
	ds_read_b128 v[206:209], v250 offset:49152
	v_mfma_f32_32x32x16_bf16 v[98:113], v[198:201], v[170:173], v[98:113]
	ds_read_b128 v[198:201], v250 offset:53248
	s_andn2_b64 vcc, exec, s[26:27]
	s_cbranch_vccnz .LBB0_283
	s_lshl_b32 s26, s28, 14
	s_add_i32 s26, s10, s26
	s_add_u32 s100, s8, s62
	s_addc_u32 s101, s9, s63
	s_add_i32 m0, s26, 0x2000
	s_nop 0
	global_load_lds_dwordx4 v214, s[100:101]
.LBB0_283:
	v_mfma_f32_32x32x16_bf16 v[114:129], v[202:205], v[170:173], v[114:129]
	ds_read_b128 v[202:205], v250 offset:57344
	v_mfma_f32_32x32x16_bf16 v[130:145], v[194:197], v[170:173], v[130:145]
	ds_read_b128 v[194:197], v250 offset:61440
	s_waitcnt lgkmcnt(0)
	v_mfma_f32_32x32x16_bf16 v[82:97], v[206:209], v[178:181], v[82:97]
	v_add_u32_e32 v250, s36, v248
	ds_read_b128 v[206:209], v250 offset:49152
	v_mfma_f32_32x32x16_bf16 v[98:113], v[198:201], v[178:181], v[98:113]
	ds_read_b128 v[198:201], v250 offset:53248
	v_cndmask_b32_e64 v224, 0, 1, s[44:45]
	v_cmp_ne_u32_e64 s[40:41], 1, v224
	s_andn2_b64 vcc, exec, s[44:45]
	s_cbranch_vccnz .LBB0_285
	s_lshl_b32 s26, s23, 14
	s_add_i32 s26, s10, s26
	s_add_u32 s100, s8, s96
	s_addc_u32 s101, s9, s97
	s_add_i32 m0, s26, 0xc000
	s_nop 0
	global_load_lds_dwordx4 v216, s[100:101]
.LBB0_285:
	v_mfma_f32_32x32x16_bf16 v[114:129], v[202:205], v[178:181], v[114:129]
	ds_read_b128 v[202:205], v250 offset:57344
	v_mfma_f32_32x32x16_bf16 v[130:145], v[194:197], v[178:181], v[130:145]
	ds_read_b128 v[194:197], v250 offset:61440
	s_waitcnt lgkmcnt(0)
	v_mfma_f32_32x32x16_bf16 v[82:97], v[206:209], v[186:189], v[82:97]
	v_mfma_f32_32x32x16_bf16 v[98:113], v[198:201], v[186:189], v[98:113]
	s_and_b64 vcc, exec, s[40:41]
	s_cbranch_vccnz .LBB0_287
	s_lshl_b32 s26, s23, 14
	s_add_i32 s26, s10, s26
	s_add_u32 s100, s8, s58
	s_addc_u32 s101, s9, s59
	s_add_i32 m0, s26, 0xe000
	s_nop 0
	global_load_lds_dwordx4 v216, s[100:101]

.LBB0_291:
	s_waitcnt lgkmcnt(0)
	v_mfma_f32_32x32x16_bf16 v[50:65], v[126:129], v[162:165], v[50:65]
	ds_read_b128 v[126:129], v0 offset:49152
	s_nop 1
	v_exp_f32_e32 v130, v82
	v_exp_f32_e32 v131, v83
	v_add_f32_e32 v132, v1, v130
	v_add_f32_e32 v133, v1, v131
	v_cvt_pk_bf16_f32 v166, v130, v131
	v_mfma_f32_32x32x16_bf16 v[34:49], v[122:125], v[162:165], v[34:49]
	ds_read_b128 v[122:125], v0 offset:53248
	v_exp_f32_e32 v134, v84
	v_exp_f32_e32 v135, v85
	s_add_i32 s21, s22, 2
	s_cmp_lt_u32 s21, s18
	v_add_f32_e32 v130, v132, v134
	v_add_f32_e32 v131, v133, v135
	v_cvt_pk_bf16_f32 v167, v134, v135
	s_cselect_b64 s[26:27], -1, 0
	s_cmp_ge_u32 s21, s18
	s_cbranch_scc1 .LBB0_293
	s_lshl_b32 s37, s28, 14
	s_add_u32 s100, s8, s80
	s_addc_u32 s101, s9, s81
	s_add_i32 m0, s10, s37
	s_nop 0
	global_load_lds_dwordx4 v214, s[100:101]
.LBB0_293:
	v_mfma_f32_32x32x16_bf16 v[18:33], v[118:121], v[162:165], v[18:33]
	ds_read_b128 v[118:121], v0 offset:57344
	v_exp_f32_e32 v132, v86
	v_exp_f32_e32 v133, v87
	v_add_f32_e32 v130, v130, v132
	v_add_f32_e32 v131, v131, v133
	v_cvt_pk_bf16_f32 v168, v132, v133
	v_mfma_f32_32x32x16_bf16 v[2:17], v[114:117], v[162:165], v[2:17]
	ds_read_b128 v[114:117], v0 offset:61440
	v_exp_f32_e32 v0, v88
	v_exp_f32_e32 v132, v89
	v_add_f32_e32 v130, v130, v0
	v_add_f32_e32 v131, v131, v132
	v_cvt_pk_bf16_f32 v169, v0, v132
	s_waitcnt lgkmcnt(0)
	v_mfma_f32_32x32x16_bf16 v[50:65], v[126:129], v[170:173], v[50:65]
	v_add_u32_e32 v0, s36, v247
	ds_read_b128 v[126:129], v0 offset:49152
	v_exp_f32_e32 v132, v90
	v_exp_f32_e32 v133, v91
	v_add_f32_e32 v130, v130, v132
	v_add_f32_e32 v131, v131, v133
	v_cvt_pk_bf16_f32 v174, v132, v133
	v_mfma_f32_32x32x16_bf16 v[34:49], v[122:125], v[170:173], v[34:49]
	ds_read_b128 v[122:125], v0 offset:53248
	v_exp_f32_e32 v132, v92
	v_exp_f32_e32 v133, v93
	v_add_f32_e32 v130, v130, v132
	v_add_f32_e32 v131, v131, v133
	s_andn2_b64 vcc, exec, s[26:27]
	v_cvt_pk_bf16_f32 v175, v132, v133
	s_cbranch_vccnz .LBB0_295
	s_lshl_b32 s26, s28, 14
	s_add_i32 s26, s10, s26
	s_add_u32 s100, s8, s62
	s_addc_u32 s101, s9, s63
	s_add_i32 m0, s26, 0x2000
	s_nop 0
	global_load_lds_dwordx4 v214, s[100:101]
.LBB0_295:
	v_mfma_f32_32x32x16_bf16 v[18:33], v[118:121], v[170:173], v[18:33]
	ds_read_b128 v[118:121], v0 offset:57344
	v_exp_f32_e32 v132, v94
	v_exp_f32_e32 v133, v95
	v_add_f32_e32 v130, v130, v132
	v_add_f32_e32 v131, v131, v133
	v_cvt_pk_bf16_f32 v176, v132, v133
	v_mfma_f32_32x32x16_bf16 v[2:17], v[114:117], v[170:173], v[2:17]
	ds_read_b128 v[114:117], v0 offset:61440
	v_exp_f32_e32 v0, v96
	v_exp_f32_e32 v132, v97
	v_add_f32_e32 v130, v130, v0
	v_add_f32_e32 v131, v131, v132
	v_cvt_pk_bf16_f32 v177, v0, v132
	s_waitcnt lgkmcnt(0)
	v_mfma_f32_32x32x16_bf16 v[50:65], v[126:129], v[178:181], v[50:65]
	v_add_u32_e32 v0, s36, v248
	ds_read_b128 v[126:129], v0 offset:49152
	v_exp_f32_e32 v132, v98
	v_exp_f32_e32 v133, v99
	v_add_f32_e32 v130, v130, v132
	v_add_f32_e32 v131, v131, v133
	v_cvt_pk_bf16_f32 v182, v132, v133
	v_mfma_f32_32x32x16_bf16 v[34:49], v[122:125], v[178:181], v[34:49]
	v_exp_f32_e32 v132, v100
	v_exp_f32_e32 v133, v101
	ds_read_b128 v[122:125], v0 offset:53248
	v_add_f32_e32 v130, v130, v132
	v_add_f32_e32 v131, v131, v133
	v_cvt_pk_bf16_f32 v183, v132, v133
	v_cndmask_b32_e64 v132, 0, 1, s[44:45]
	v_cmp_ne_u32_e64 s[40:41], 1, v132
	s_andn2_b64 vcc, exec, s[44:45]
	s_cbranch_vccnz .LBB0_297
	s_lshl_b32 s26, s23, 14
	s_add_i32 s26, s10, s26
	s_add_u32 s100, s8, s96
	s_addc_u32 s101, s9, s97
	s_add_i32 m0, s26, 0xc000
	s_nop 0
	global_load_lds_dwordx4 v216, s[100:101]
.LBB0_297:
	v_mfma_f32_32x32x16_bf16 v[18:33], v[118:121], v[178:181], v[18:33]
	ds_read_b128 v[118:121], v0 offset:57344
	v_exp_f32_e32 v132, v102
	v_exp_f32_e32 v133, v103
	v_add_f32_e32 v130, v130, v132
	v_add_f32_e32 v131, v131, v133
	v_cvt_pk_bf16_f32 v184, v132, v133
	v_mfma_f32_32x32x16_bf16 v[2:17], v[114:117], v[178:181], v[2:17]
	ds_read_b128 v[114:117], v0 offset:61440
	v_exp_f32_e32 v0, v104
	v_exp_f32_e32 v132, v105
	v_add_f32_e32 v130, v130, v0
	v_add_f32_e32 v131, v131, v132
	v_cvt_pk_bf16_f32 v185, v0, v132
	s_waitcnt lgkmcnt(0)
	v_mfma_f32_32x32x16_bf16 v[50:65], v[126:129], v[186:189], v[50:65]
	v_exp_f32_e32 v0, v106
	v_exp_f32_e32 v126, v107
	v_add_f32_e32 v127, v130, v0
	v_add_f32_e32 v128, v131, v126
	v_cvt_pk_bf16_f32 v190, v0, v126
	v_mfma_f32_32x32x16_bf16 v[34:49], v[122:125], v[186:189], v[34:49]
	v_exp_f32_e32 v123, v108
	v_exp_f32_e32 v124, v109
	v_add_f32_e32 v0, v127, v123
	v_add_f32_e32 v122, v128, v124
	s_and_b64 vcc, exec, s[40:41]
	v_cvt_pk_bf16_f32 v191, v123, v124
	s_cbranch_vccnz .LBB0_299
	s_lshl_b32 s26, s23, 14
	s_add_i32 s26, s10, s26
	s_add_u32 s100, s8, s58
	s_addc_u32 s101, s9, s59
	s_add_i32 m0, s26, 0xe000
	s_nop 0
	global_load_lds_dwordx4 v216, s[100:101]

.LBB0_311:
	s_add_i32 s26, s31, 1
	s_cmp_lg_u32 s31, 2
	s_cselect_b32 s31, s26, 0
	s_add_i32 s26, s28, 1
	s_cmp_lg_u32 s28, 2
	s_cselect_b32 s28, s26, 0
	s_add_i32 s26, s33, 1
	s_cmp_lg_u32 s33, 2
	s_cselect_b32 s33, s26, 0
	s_add_i32 s26, s23, 1
	s_barrier
	s_cmp_lg_u32 s23, 2
	s_cselect_b32 s23, s26, 0
	s_cmp_lt_u32 s22, s19
	s_mov_b64 s[26:27], -1
	s_cbranch_scc1 .LBB0_317
	s_add_i32 s26, s22, 3
	s_cmp_gt_u32 s26, s17
	s_cbranch_scc1 .LBB0_314
	s_lshl_b32 s26, s28, 14
	s_add_i32 s26, s10, s26
	s_add_i32 s27, s26, 0x2000
	s_add_u32 s100, s8, s50
	s_addc_u32 s101, s9, s51
	s_mov_b32 m0, s26
	s_nop 0
	global_load_lds_dwordx4 v214, s[100:101]
	s_add_u32 s100, s8, s4
	s_addc_u32 s101, s9, s5
	s_mov_b32 m0, s27
	s_nop 0
	global_load_lds_dwordx4 v214, s[100:101]
.LBB0_314:
	s_andn2_b64 vcc, exec, s[44:45]
	s_cbranch_vccnz .LBB0_316
	s_lshl_b32 s26, s23, 14
	s_add_i32 s26, s10, s26
	s_add_u32 s100, s8, s0
	s_addc_u32 s101, s9, s1
	s_add_i32 m0, s26, 0xc000
	s_add_i32 s26, s26, 0xe000
	global_load_lds_dwordx4 v216, s[100:101]
	s_add_u32 s100, s8, s52
	s_addc_u32 s101, s9, s53
	s_mov_b32 m0, s26
	s_nop 0
	global_load_lds_dwordx4 v216, s[100:101]

.LBB0_317:
	s_and_b64 vcc, exec, s[26:27]
	s_cbranch_vccz .LBB0_343
	s_lshl_b32 s26, s33, 14
	s_add_i32 s37, s22, 1
	s_add_i32 s36, s26, 0
	s_mov_b64 s[26:27], -1
	s_cmp_ge_u32 s37, s19
	v_add_u32_e32 v212, s36, v245
	v_add_u32_e32 v0, s36, v246
	s_cbranch_scc0 .LBB0_328
	ds_read_b128 v[98:101], v212 offset:49152
	ds_read_b128 v[114:117], v212 offset:53248
	ds_read_b128 v[130:133], v212 offset:57344
	ds_read_b128 v[194:197], v212 offset:61440
	s_waitcnt lgkmcnt(0)
	v_mfma_f32_32x32x16_bf16 v[82:97], v[98:101], v[166:169], v[50:65]
	ds_read_b128 v[206:209], v0 offset:49152
	v_mfma_f32_32x32x16_bf16 v[98:113], v[114:117], v[166:169], v[34:49]
	ds_read_b128 v[198:201], v0 offset:53248
	s_add_i32 s37, s22, 3
	s_cmp_le_u32 s37, s17
	s_cselect_b64 s[26:27], -1, 0
	s_cmp_gt_u32 s37, s17
	s_cbranch_scc1 .LBB0_321
	s_lshl_b32 s37, s28, 14
	s_add_u32 s100, s8, s50
	s_addc_u32 s101, s9, s51
	s_add_i32 m0, s10, s37
	s_nop 0
	global_load_lds_dwordx4 v214, s[100:101]
.LBB0_321:
	v_mfma_f32_32x32x16_bf16 v[114:129], v[130:133], v[166:169], v[18:33]
	ds_read_b128 v[202:205], v0 offset:57344
	v_mfma_f32_32x32x16_bf16 v[130:145], v[194:197], v[166:169], v[2:17]
	ds_read_b128 v[194:197], v0 offset:61440
	s_waitcnt lgkmcnt(0)
	v_mfma_f32_32x32x16_bf16 v[82:97], v[206:209], v[174:177], v[82:97]
	v_add_u32_e32 v250, s36, v247
	ds_read_b128 v[206:209], v250 offset:49152
	v_mfma_f32_32x32x16_bf16 v[98:113], v[198:201], v[174:177], v[98:113]
	ds_read_b128 v[198:201], v250 offset:53248
	s_andn2_b64 vcc, exec, s[26:27]
	s_cbranch_vccnz .LBB0_323
	s_lshl_b32 s26, s28, 14
	s_add_i32 s26, s10, s26
	s_add_u32 s100, s8, s4
	s_addc_u32 s101, s9, s5
	s_add_i32 m0, s26, 0x2000
	s_nop 0
	global_load_lds_dwordx4 v214, s[100:101]
.LBB0_323:
	v_mfma_f32_32x32x16_bf16 v[114:129], v[202:205], v[174:177], v[114:129]
	ds_read_b128 v[202:205], v250 offset:57344
	v_mfma_f32_32x32x16_bf16 v[130:145], v[194:197], v[174:177], v[130:145]
	ds_read_b128 v[194:197], v250 offset:61440
	s_waitcnt lgkmcnt(0)
	v_mfma_f32_32x32x16_bf16 v[82:97], v[206:209], v[182:185], v[82:97]
	v_add_u32_e32 v250, s36, v248
	ds_read_b128 v[206:209], v250 offset:49152
	v_mfma_f32_32x32x16_bf16 v[98:113], v[198:201], v[182:185], v[98:113]
	ds_read_b128 v[198:201], v250 offset:53248
	v_cndmask_b32_e64 v224, 0, 1, s[44:45]
	v_cmp_ne_u32_e64 s[40:41], 1, v224
	s_andn2_b64 vcc, exec, s[44:45]
	s_cbranch_vccnz .LBB0_325
	s_lshl_b32 s26, s23, 14
	s_add_i32 s26, s10, s26
	s_add_u32 s100, s8, s0
	s_addc_u32 s101, s9, s1
	s_add_i32 m0, s26, 0xc000
	s_nop 0
	global_load_lds_dwordx4 v216, s[100:101]
.LBB0_325:
	v_mfma_f32_32x32x16_bf16 v[114:129], v[202:205], v[182:185], v[114:129]
	ds_read_b128 v[202:205], v250 offset:57344
	v_mfma_f32_32x32x16_bf16 v[130:145], v[194:197], v[182:185], v[130:145]
	ds_read_b128 v[194:197], v250 offset:61440
	s_waitcnt lgkmcnt(0)
	v_mfma_f32_32x32x16_bf16 v[82:97], v[206:209], v[190:193], v[82:97]
	v_mfma_f32_32x32x16_bf16 v[98:113], v[198:201], v[190:193], v[98:113]
	s_and_b64 vcc, exec, s[40:41]
	s_cbranch_vccnz .LBB0_327
	s_lshl_b32 s26, s23, 14
	s_add_i32 s26, s10, s26
	s_add_u32 s100, s8, s52
	s_addc_u32 s101, s9, s53
	s_add_i32 m0, s26, 0xe000
	s_nop 0
	global_load_lds_dwordx4 v216, s[100:101]

.LBB0_335:
	v_mfma_f32_32x32x16_bf16 v[18:33], v[118:121], v[174:177], v[18:33]
	ds_read_b128 v[118:121], v0 offset:57344
	v_exp_f32_e32 v130, v94
	v_exp_f32_e32 v131, v95
	v_add_f32_e32 v132, v132, v130
	v_add_f32_e32 v133, v133, v131
	v_cvt_pk_bf16_f32 v172, v130, v131
	v_mfma_f32_32x32x16_bf16 v[2:17], v[114:117], v[174:177], v[2:17]
	ds_read_b128 v[114:117], v0 offset:61440
	v_exp_f32_e32 v0, v96
	v_exp_f32_e32 v130, v97
	v_add_f32_e32 v131, v132, v0
	v_add_f32_e32 v132, v133, v130
	v_cvt_pk_bf16_f32 v173, v0, v130
	s_waitcnt lgkmcnt(0)
	v_mfma_f32_32x32x16_bf16 v[50:65], v[126:129], v[182:185], v[50:65]
	v_add_u32_e32 v0, s36, v248
	ds_read_b128 v[126:129], v0 offset:49152
	v_exp_f32_e32 v130, v98
	v_exp_f32_e32 v133, v99
	v_add_f32_e32 v131, v131, v130
	v_add_f32_e32 v134, v132, v133
	v_cvt_pk_bf16_f32 v178, v130, v133
	v_mfma_f32_32x32x16_bf16 v[34:49], v[122:125], v[182:185], v[34:49]
	v_exp_f32_e32 v130, v100
	v_exp_f32_e32 v135, v101
	ds_read_b128 v[122:125], v0 offset:53248
	v_add_f32_e32 v132, v131, v130
	v_add_f32_e32 v133, v134, v135
	v_cvt_pk_bf16_f32 v179, v130, v135
	v_cndmask_b32_e64 v130, 0, 1, s[44:45]
	v_cmp_ne_u32_e64 s[40:41], 1, v130
	s_andn2_b64 vcc, exec, s[44:45]
	v_lshl_add_u64 v[130:131], s[8:9], 0, v[216:217]
	s_cbranch_vccnz .LBB0_337
	s_lshl_b32 s22, s23, 14
	s_add_i32 s22, s10, s22
	s_add_u32 s100, s8, s0
	s_addc_u32 s101, s9, s1
	s_add_i32 m0, s22, 0xc000
	s_nop 0
	global_load_lds_dwordx4 v216, s[100:101]
